# SwiGLU epilogue: 16 dwordx2 stores -> 8 dwordx4 stores via v_permlane16_swap pairing of two 16-row blocks (same bytes, same addresses)
# speedup vs baseline: 1.0221x; 1.0221x over previous
.LBB0_686:
	s_or_b64 exec, exec, s[38:39]
	v_bfe_u32 v208, v154, 4, 1
	v_mul_u32_u24_e32 v208, 0x15ff8, v208
	v_mov_b32_e32 v209, 0
	v_mul_f32_e32 v131, 0xbfb8aa3b, v124
	v_exp_f32_e32 v132, v131
	v_mul_f32_e32 v131, 0xbfb8aa3b, v125
	v_exp_f32_e32 v133, v131
	v_or_b32_e32 v130, s30, v146
	s_lshl_b32 s38, s56, 7
	v_lshlrev_b32_e32 v131, 4, v145
	v_pk_add_f32 v[132:133], v[132:133], 1.0 op_sel_hi:[1,0]
	v_lshlrev_b32_e32 v134, 2, v144
	v_or3_b32 v134, v131, s38, v134
	v_add_u32_e32 v130, v130, v147
	v_ashrrev_i32_e32 v135, 31, v134
	v_div_scale_f32 v139, s[30:31], v132, v132, v124
	v_rcp_f32_e32 v140, v139
	v_rcp_f32_e32 v131, v133
	s_nop 0
	v_mul_f32_e32 v125, v125, v131
	v_fma_f32 v131, -v139, v140, 1.0
	v_fmac_f32_e32 v140, v131, v140
	v_mul_f32_e32 v136, 0xbfb8aa3b, v126
	v_mul_f32_e32 v137, 0xbfb8aa3b, v127
	v_exp_f32_e32 v136, v136
	v_exp_f32_e32 v137, v137
	v_rcp_f32_e32 v131, v132
	s_nop 0
	v_mul_f32_e32 v124, v124, v131
	v_pk_add_f32 v[136:137], v[136:137], 1.0 op_sel_hi:[1,0]
	v_pk_mul_f32 v[120:121], v[120:121], v[124:125]
	v_div_scale_f32 v133, s[30:31], v137, v137, v127
	v_rcp_f32_e32 v138, v133
	v_cvt_pk_bf16_f32 v176, v120, v121
	v_fma_f32 v120, -v133, v138, 1.0
	v_fmac_f32_e32 v138, v120, v138
	v_rcp_f32_e32 v120, v137
	s_nop 0
	v_mul_f32_e32 v121, v127, v120
	v_rcp_f32_e32 v120, v136
	s_nop 0
	v_mul_f32_e32 v120, v126, v120
	v_pk_mul_f32 v[120:121], v[122:123], v[120:121]
	v_lshlrev_b64 v[122:123], 1, v[134:135]
	v_cvt_pk_bf16_f32 v177, v120, v121
	v_mov_b64_e32 v[120:121], s[6:7]
	v_mad_i64_i32 v[124:125], s[30:31], v130, s53, v[120:121]
	v_lshl_add_u64 v[124:125], v[124:125], 0, v[122:123]
	v_lshl_add_u64 v[124:125], v[124:125], 0, v[208:209]
	v_mul_f32_e32 v126, 0xbfb8aa3b, v116
	v_mul_f32_e32 v127, 0xbfb8aa3b, v117
	v_exp_f32_e32 v126, v126
	v_exp_f32_e32 v127, v127
	v_or_b32_e32 v134, 16, v130
	v_pk_add_f32 v[126:127], v[126:127], 1.0 op_sel_hi:[1,0]
	s_nop 0
	v_div_scale_f32 v136, s[30:31], v126, v126, v116
	v_rcp_f32_e32 v137, v136
	v_rcp_f32_e32 v131, v127
	s_nop 0
	v_mul_f32_e32 v117, v117, v131
	v_fma_f32 v127, -v136, v137, 1.0
	v_fmac_f32_e32 v137, v127, v137
	v_mul_f32_e32 v132, 0xbfb8aa3b, v118
	v_mul_f32_e32 v133, 0xbfb8aa3b, v119
	v_exp_f32_e32 v132, v132
	v_exp_f32_e32 v133, v133
	v_rcp_f32_e32 v127, v126
	s_nop 0
	v_mul_f32_e32 v116, v116, v127
	v_pk_add_f32 v[132:133], v[132:133], 1.0 op_sel_hi:[1,0]
	v_pk_mul_f32 v[112:113], v[112:113], v[116:117]
	v_div_scale_f32 v131, s[30:31], v133, v133, v119
	v_rcp_f32_e32 v135, v131
	v_cvt_pk_bf16_f32 v178, v112, v113
	v_fma_f32 v112, -v131, v135, 1.0
	v_fmac_f32_e32 v135, v112, v135
	v_rcp_f32_e32 v112, v133
	s_nop 0
	v_mul_f32_e32 v113, v119, v112
	v_rcp_f32_e32 v112, v132
	s_nop 0
	v_mul_f32_e32 v112, v118, v112
	v_pk_mul_f32 v[112:113], v[114:115], v[112:113]
	s_nop 0
	v_cvt_pk_bf16_f32 v179, v112, v113
	s_nop 1
	v_permlane16_swap_b32_e32 v176, v178
	v_permlane16_swap_b32_e32 v177, v179
	global_store_dwordx4 v[124:125], v[176:179], off
	v_mul_f32_e32 v114, 0xbfb8aa3b, v108
	v_mul_f32_e32 v115, 0xbfb8aa3b, v109
	v_exp_f32_e32 v114, v114
	v_exp_f32_e32 v115, v115
	v_or_b32_e32 v118, 32, v130
	v_pk_add_f32 v[114:115], v[114:115], 1.0 op_sel_hi:[1,0]
	s_nop 0
	v_rcp_f32_e32 v116, v115
	s_nop 0
	v_mul_f32_e32 v109, v109, v116
	v_mul_f32_e32 v117, 0xbfb8aa3b, v111
	v_mul_f32_e32 v116, 0xbfb8aa3b, v110
	v_exp_f32_e32 v116, v116
	v_exp_f32_e32 v117, v117
	v_rcp_f32_e32 v115, v114
	s_nop 0
	v_mul_f32_e32 v108, v108, v115
	v_pk_add_f32 v[116:117], v[116:117], 1.0 op_sel_hi:[1,0]
	v_pk_mul_f32 v[104:105], v[104:105], v[108:109]
	s_nop 0
	v_cvt_pk_bf16_f32 v180, v104, v105
	v_rcp_f32_e32 v104, v117
	s_nop 0
	v_mul_f32_e32 v105, v111, v104
	v_rcp_f32_e32 v104, v116
	s_nop 0
	v_mul_f32_e32 v104, v110, v104
	v_pk_mul_f32 v[104:105], v[106:107], v[104:105]
	s_nop 0
	v_cvt_pk_bf16_f32 v181, v104, v105
	v_mad_i64_i32 v[104:105], s[30:31], v118, s53, v[120:121]
	v_lshl_add_u64 v[104:105], v[104:105], 0, v[122:123]
	v_lshl_add_u64 v[104:105], v[104:105], 0, v[208:209]
	v_mul_f32_e32 v106, 0xbfb8aa3b, v100
	v_mul_f32_e32 v107, 0xbfb8aa3b, v101
	v_exp_f32_e32 v106, v106
	v_exp_f32_e32 v107, v107
	v_or_b32_e32 v110, 48, v130
	v_pk_add_f32 v[106:107], v[106:107], 1.0 op_sel_hi:[1,0]
	s_nop 0
	v_rcp_f32_e32 v108, v107
	s_nop 0
	v_mul_f32_e32 v101, v101, v108
	v_mul_f32_e32 v109, 0xbfb8aa3b, v103
	v_mul_f32_e32 v108, 0xbfb8aa3b, v102
	v_exp_f32_e32 v108, v108
	v_exp_f32_e32 v109, v109
	v_rcp_f32_e32 v107, v106
	s_nop 0
	v_mul_f32_e32 v100, v100, v107
	v_pk_add_f32 v[108:109], v[108:109], 1.0 op_sel_hi:[1,0]
	v_pk_mul_f32 v[96:97], v[96:97], v[100:101]
	s_nop 0
	v_cvt_pk_bf16_f32 v182, v96, v97
	v_rcp_f32_e32 v96, v109
	s_nop 0
	v_mul_f32_e32 v97, v103, v96
	v_rcp_f32_e32 v96, v108
	s_nop 0
	v_mul_f32_e32 v96, v102, v96
	v_pk_mul_f32 v[96:97], v[98:99], v[96:97]
	s_nop 0
	v_cvt_pk_bf16_f32 v183, v96, v97
	s_nop 1
	v_permlane16_swap_b32_e32 v180, v182
	v_permlane16_swap_b32_e32 v181, v183
	global_store_dwordx4 v[104:105], v[180:183], off
	v_mul_f32_e32 v98, 0xbfb8aa3b, v92
	v_mul_f32_e32 v99, 0xbfb8aa3b, v93
	v_exp_f32_e32 v98, v98
	v_exp_f32_e32 v99, v99
	s_nop 0
	v_pk_add_f32 v[98:99], v[98:99], 1.0 op_sel_hi:[1,0]
	s_nop 0
	v_rcp_f32_e32 v100, v99
	s_nop 0
	v_mul_f32_e32 v93, v93, v100
	v_mul_f32_e32 v101, 0xbfb8aa3b, v95
	v_mul_f32_e32 v100, 0xbfb8aa3b, v94
	v_exp_f32_e32 v100, v100
	v_exp_f32_e32 v101, v101
	v_rcp_f32_e32 v99, v98
	s_nop 0
	v_mul_f32_e32 v92, v92, v99
	v_pk_add_f32 v[100:101], v[100:101], 1.0 op_sel_hi:[1,0]
	v_pk_mul_f32 v[88:89], v[88:89], v[92:93]
	s_nop 0
	v_cvt_pk_bf16_f32 v184, v88, v89
	v_rcp_f32_e32 v89, v101
	s_nop 0
	v_mul_f32_e32 v93, v95, v89
	v_rcp_f32_e32 v89, v100
	s_nop 0
	v_mul_f32_e32 v92, v94, v89
	v_pk_mul_f32 v[90:91], v[90:91], v[92:93]
	s_nop 0
	v_cvt_pk_bf16_f32 v185, v90, v91
	v_mul_f32_e32 v88, 0xbfb8aa3b, v84
	v_mul_f32_e32 v89, 0xbfb8aa3b, v85
	v_exp_f32_e32 v88, v88
	v_exp_f32_e32 v89, v89
	s_nop 0
	v_pk_add_f32 v[88:89], v[88:89], 1.0 op_sel_hi:[1,0]
	s_nop 0
	v_rcp_f32_e32 v90, v89
	s_nop 0
	v_mul_f32_e32 v85, v85, v90
	v_mul_f32_e32 v91, 0xbfb8aa3b, v87
	v_mul_f32_e32 v90, 0xbfb8aa3b, v86
	v_exp_f32_e32 v90, v90
	v_exp_f32_e32 v91, v91
	v_rcp_f32_e32 v89, v88
	s_nop 0
	v_mul_f32_e32 v84, v84, v89
	v_pk_add_f32 v[90:91], v[90:91], 1.0 op_sel_hi:[1,0]
	v_pk_mul_f32 v[80:81], v[80:81], v[84:85]
	s_nop 0
	v_cvt_pk_bf16_f32 v186, v80, v81
	v_rcp_f32_e32 v81, v91
	s_nop 0
	v_mul_f32_e32 v85, v87, v81
	v_rcp_f32_e32 v81, v90
	s_nop 0
	v_mul_f32_e32 v84, v86, v81
	v_pk_mul_f32 v[82:83], v[82:83], v[84:85]
	s_nop 0
	v_cvt_pk_bf16_f32 v187, v82, v83
	s_nop 1
	v_permlane16_swap_b32_e32 v184, v186
	v_permlane16_swap_b32_e32 v185, v187
	global_store_dwordx4 v[124:125], v[184:187], off offset:128
	v_mul_f32_e32 v80, 0xbfb8aa3b, v76
	v_mul_f32_e32 v81, 0xbfb8aa3b, v77
	v_exp_f32_e32 v80, v80
	v_exp_f32_e32 v81, v81
	s_nop 0
	v_pk_add_f32 v[80:81], v[80:81], 1.0 op_sel_hi:[1,0]
	s_nop 0
	v_rcp_f32_e32 v82, v81
	s_nop 0
	v_mul_f32_e32 v77, v77, v82
	v_mul_f32_e32 v83, 0xbfb8aa3b, v79
	v_mul_f32_e32 v82, 0xbfb8aa3b, v78
	v_exp_f32_e32 v82, v82
	v_exp_f32_e32 v83, v83
	v_rcp_f32_e32 v81, v80
	s_nop 0
	v_mul_f32_e32 v76, v76, v81
	v_pk_add_f32 v[82:83], v[82:83], 1.0 op_sel_hi:[1,0]
	v_pk_mul_f32 v[72:73], v[72:73], v[76:77]
	s_nop 0
	v_cvt_pk_bf16_f32 v188, v72, v73
	v_rcp_f32_e32 v73, v83
	s_nop 0
	v_mul_f32_e32 v77, v79, v73
	v_rcp_f32_e32 v73, v82
	s_nop 0
	v_mul_f32_e32 v76, v78, v73
	v_pk_mul_f32 v[74:75], v[74:75], v[76:77]
	s_nop 0
	v_cvt_pk_bf16_f32 v189, v74, v75
	v_mul_f32_e32 v72, 0xbfb8aa3b, v68
	v_mul_f32_e32 v73, 0xbfb8aa3b, v69
	v_exp_f32_e32 v72, v72
	v_exp_f32_e32 v73, v73
	s_nop 0
	v_pk_add_f32 v[72:73], v[72:73], 1.0 op_sel_hi:[1,0]
	s_nop 0
	v_rcp_f32_e32 v74, v73
	s_nop 0
	v_mul_f32_e32 v69, v69, v74
	v_mul_f32_e32 v75, 0xbfb8aa3b, v71
	v_mul_f32_e32 v74, 0xbfb8aa3b, v70
	v_exp_f32_e32 v74, v74
	v_exp_f32_e32 v75, v75
	v_rcp_f32_e32 v73, v72
	s_nop 0
	v_mul_f32_e32 v68, v68, v73
	v_pk_add_f32 v[74:75], v[74:75], 1.0 op_sel_hi:[1,0]
	v_pk_mul_f32 v[64:65], v[64:65], v[68:69]
	s_nop 0
	v_cvt_pk_bf16_f32 v190, v64, v65
	v_rcp_f32_e32 v65, v75
	s_nop 0
	v_mul_f32_e32 v69, v71, v65
	v_rcp_f32_e32 v65, v74
	s_nop 0
	v_mul_f32_e32 v68, v70, v65
	v_pk_mul_f32 v[66:67], v[66:67], v[68:69]
	s_nop 0
	v_cvt_pk_bf16_f32 v191, v66, v67
	s_nop 1
	v_permlane16_swap_b32_e32 v188, v190
	v_permlane16_swap_b32_e32 v189, v191
	global_store_dwordx4 v[104:105], v[188:191], off offset:128
	v_mul_f32_e32 v64, 0xbfb8aa3b, v60
	v_mul_f32_e32 v65, 0xbfb8aa3b, v61
	v_exp_f32_e32 v64, v64
	v_exp_f32_e32 v65, v65
	v_add_u32_e32 v68, 0x80, v130
	v_pk_add_f32 v[64:65], v[64:65], 1.0 op_sel_hi:[1,0]
	s_nop 0
	v_rcp_f32_e32 v66, v65
	s_nop 0
	v_mul_f32_e32 v61, v61, v66
	v_mul_f32_e32 v67, 0xbfb8aa3b, v63
	v_mul_f32_e32 v66, 0xbfb8aa3b, v62
	v_exp_f32_e32 v66, v66
	v_exp_f32_e32 v67, v67
	v_rcp_f32_e32 v65, v64
	s_nop 0
	v_mul_f32_e32 v60, v60, v65
	v_pk_add_f32 v[66:67], v[66:67], 1.0 op_sel_hi:[1,0]
	v_pk_mul_f32 v[56:57], v[56:57], v[60:61]
	s_nop 0
	v_cvt_pk_bf16_f32 v192, v56, v57
	v_rcp_f32_e32 v56, v67
	s_nop 0
	v_mul_f32_e32 v57, v63, v56
	v_rcp_f32_e32 v56, v66
	s_nop 0
	v_mul_f32_e32 v56, v62, v56
	v_pk_mul_f32 v[56:57], v[58:59], v[56:57]
	s_nop 0
	v_cvt_pk_bf16_f32 v193, v56, v57
	v_mad_i64_i32 v[56:57], s[30:31], v68, s53, v[120:121]
	v_lshl_add_u64 v[56:57], v[56:57], 0, v[122:123]
	v_lshl_add_u64 v[56:57], v[56:57], 0, v[208:209]
	v_mul_f32_e32 v58, 0xbfb8aa3b, v52
	v_mul_f32_e32 v59, 0xbfb8aa3b, v53
	v_exp_f32_e32 v58, v58
	v_exp_f32_e32 v59, v59
	v_add_u32_e32 v62, 0x90, v130
	v_pk_add_f32 v[58:59], v[58:59], 1.0 op_sel_hi:[1,0]
	s_nop 0
	v_rcp_f32_e32 v60, v59
	s_nop 0
	v_mul_f32_e32 v53, v53, v60
	v_mul_f32_e32 v61, 0xbfb8aa3b, v55
	v_mul_f32_e32 v60, 0xbfb8aa3b, v54
	v_exp_f32_e32 v60, v60
	v_exp_f32_e32 v61, v61
	v_rcp_f32_e32 v59, v58
	s_nop 0
	v_mul_f32_e32 v52, v52, v59
	v_pk_add_f32 v[60:61], v[60:61], 1.0 op_sel_hi:[1,0]
	v_pk_mul_f32 v[48:49], v[48:49], v[52:53]
	s_nop 0
	v_cvt_pk_bf16_f32 v194, v48, v49
	v_rcp_f32_e32 v48, v61
	s_nop 0
	v_mul_f32_e32 v49, v55, v48
	v_rcp_f32_e32 v48, v60
	s_nop 0
	v_mul_f32_e32 v48, v54, v48
	v_pk_mul_f32 v[48:49], v[50:51], v[48:49]
	s_nop 0
	v_cvt_pk_bf16_f32 v195, v48, v49
	s_nop 1
	v_permlane16_swap_b32_e32 v192, v194
	v_permlane16_swap_b32_e32 v193, v195
	global_store_dwordx4 v[56:57], v[192:195], off
	v_mul_f32_e32 v50, 0xbfb8aa3b, v44
	v_mul_f32_e32 v51, 0xbfb8aa3b, v45
	v_exp_f32_e32 v50, v50
	v_exp_f32_e32 v51, v51
	v_add_u32_e32 v54, 0xa0, v130
	v_pk_add_f32 v[50:51], v[50:51], 1.0 op_sel_hi:[1,0]
	s_nop 0
	v_rcp_f32_e32 v52, v51
	s_nop 0
	v_mul_f32_e32 v45, v45, v52
	v_mul_f32_e32 v53, 0xbfb8aa3b, v47
	v_mul_f32_e32 v52, 0xbfb8aa3b, v46
	v_exp_f32_e32 v52, v52
	v_exp_f32_e32 v53, v53
	v_rcp_f32_e32 v51, v50
	s_nop 0
	v_mul_f32_e32 v44, v44, v51
	v_pk_add_f32 v[52:53], v[52:53], 1.0 op_sel_hi:[1,0]
	v_pk_mul_f32 v[40:41], v[40:41], v[44:45]
	s_nop 0
	v_cvt_pk_bf16_f32 v196, v40, v41
	v_rcp_f32_e32 v40, v53
	s_nop 0
	v_mul_f32_e32 v41, v47, v40
	v_rcp_f32_e32 v40, v52
	s_nop 0
	v_mul_f32_e32 v40, v46, v40
	v_pk_mul_f32 v[40:41], v[42:43], v[40:41]
	s_nop 0
	v_cvt_pk_bf16_f32 v197, v40, v41
	v_mad_i64_i32 v[40:41], s[30:31], v54, s53, v[120:121]
	v_lshl_add_u64 v[40:41], v[40:41], 0, v[122:123]
	v_lshl_add_u64 v[40:41], v[40:41], 0, v[208:209]
	v_mul_f32_e32 v42, 0xbfb8aa3b, v36
	v_mul_f32_e32 v43, 0xbfb8aa3b, v37
	v_exp_f32_e32 v42, v42
	v_exp_f32_e32 v43, v43
	v_add_u32_e32 v46, 0xb0, v130
	v_pk_add_f32 v[42:43], v[42:43], 1.0 op_sel_hi:[1,0]
	s_nop 0
	v_rcp_f32_e32 v44, v43
	s_nop 0
	v_mul_f32_e32 v37, v37, v44
	v_mul_f32_e32 v45, 0xbfb8aa3b, v39
	v_mul_f32_e32 v44, 0xbfb8aa3b, v38
	v_exp_f32_e32 v44, v44
	v_exp_f32_e32 v45, v45
	v_rcp_f32_e32 v43, v42
	s_nop 0
	v_mul_f32_e32 v36, v36, v43
	v_pk_add_f32 v[44:45], v[44:45], 1.0 op_sel_hi:[1,0]
	v_pk_mul_f32 v[32:33], v[32:33], v[36:37]
	s_nop 0
	v_cvt_pk_bf16_f32 v198, v32, v33
	v_rcp_f32_e32 v32, v45
	s_nop 0
	v_mul_f32_e32 v33, v39, v32
	v_rcp_f32_e32 v32, v44
	s_nop 0
	v_mul_f32_e32 v32, v38, v32
	v_pk_mul_f32 v[32:33], v[34:35], v[32:33]
	s_nop 0
	v_cvt_pk_bf16_f32 v199, v32, v33
	s_nop 1
	v_permlane16_swap_b32_e32 v196, v198
	v_permlane16_swap_b32_e32 v197, v199
	global_store_dwordx4 v[40:41], v[196:199], off
	v_mul_f32_e32 v34, 0xbfb8aa3b, v28
	v_mul_f32_e32 v35, 0xbfb8aa3b, v29
	v_exp_f32_e32 v34, v34
	v_exp_f32_e32 v35, v35
	s_nop 0
	v_pk_add_f32 v[34:35], v[34:35], 1.0 op_sel_hi:[1,0]
	s_nop 0
	v_rcp_f32_e32 v36, v35
	s_nop 0
	v_mul_f32_e32 v29, v29, v36
	v_mul_f32_e32 v37, 0xbfb8aa3b, v31
	v_mul_f32_e32 v36, 0xbfb8aa3b, v30
	v_exp_f32_e32 v36, v36
	v_exp_f32_e32 v37, v37
	v_rcp_f32_e32 v35, v34
	s_nop 0
	v_mul_f32_e32 v28, v28, v35
	v_pk_add_f32 v[36:37], v[36:37], 1.0 op_sel_hi:[1,0]
	v_pk_mul_f32 v[24:25], v[24:25], v[28:29]
	s_nop 0
	v_cvt_pk_bf16_f32 v200, v24, v25
	v_rcp_f32_e32 v25, v37
	s_nop 0
	v_mul_f32_e32 v29, v31, v25
	v_rcp_f32_e32 v25, v36
	s_nop 0
	v_mul_f32_e32 v28, v30, v25
	v_pk_mul_f32 v[26:27], v[26:27], v[28:29]
	s_nop 0
	v_cvt_pk_bf16_f32 v201, v26, v27
	v_mul_f32_e32 v24, 0xbfb8aa3b, v20
	v_mul_f32_e32 v25, 0xbfb8aa3b, v21
	v_exp_f32_e32 v24, v24
	v_exp_f32_e32 v25, v25
	s_nop 0
	v_pk_add_f32 v[24:25], v[24:25], 1.0 op_sel_hi:[1,0]
	s_nop 0
	v_rcp_f32_e32 v26, v25
	s_nop 0
	v_mul_f32_e32 v21, v21, v26
	v_mul_f32_e32 v27, 0xbfb8aa3b, v23
	v_mul_f32_e32 v26, 0xbfb8aa3b, v22
	v_exp_f32_e32 v26, v26
	v_exp_f32_e32 v27, v27
	v_rcp_f32_e32 v25, v24
	s_nop 0
	v_mul_f32_e32 v20, v20, v25
	v_pk_add_f32 v[26:27], v[26:27], 1.0 op_sel_hi:[1,0]
	v_pk_mul_f32 v[16:17], v[16:17], v[20:21]
	s_nop 0
	v_cvt_pk_bf16_f32 v202, v16, v17
	v_rcp_f32_e32 v17, v27
	s_nop 0
	v_mul_f32_e32 v21, v23, v17
	v_rcp_f32_e32 v17, v26
	s_nop 0
	v_mul_f32_e32 v20, v22, v17
	v_pk_mul_f32 v[18:19], v[18:19], v[20:21]
	s_nop 0
	v_cvt_pk_bf16_f32 v203, v18, v19
	s_nop 1
	v_permlane16_swap_b32_e32 v200, v202
	v_permlane16_swap_b32_e32 v201, v203
	global_store_dwordx4 v[56:57], v[200:203], off offset:128
	v_mul_f32_e32 v16, 0xbfb8aa3b, v12
	v_mul_f32_e32 v17, 0xbfb8aa3b, v13
	v_exp_f32_e32 v16, v16
	v_exp_f32_e32 v17, v17
	s_nop 0
	v_pk_add_f32 v[16:17], v[16:17], 1.0 op_sel_hi:[1,0]
	s_nop 0
	v_rcp_f32_e32 v18, v17
	s_nop 0
	v_mul_f32_e32 v13, v13, v18
	v_mul_f32_e32 v19, 0xbfb8aa3b, v15
	v_mul_f32_e32 v18, 0xbfb8aa3b, v14
	v_exp_f32_e32 v18, v18
	v_exp_f32_e32 v19, v19
	v_rcp_f32_e32 v17, v16
	s_nop 0
	v_mul_f32_e32 v12, v12, v17
	v_pk_add_f32 v[18:19], v[18:19], 1.0 op_sel_hi:[1,0]
	v_pk_mul_f32 v[8:9], v[8:9], v[12:13]
	s_nop 0
	v_cvt_pk_bf16_f32 v204, v8, v9
	v_rcp_f32_e32 v9, v19
	s_nop 0
	v_mul_f32_e32 v13, v15, v9
	v_rcp_f32_e32 v9, v18
	s_nop 0
	v_mul_f32_e32 v12, v14, v9
	v_pk_mul_f32 v[10:11], v[10:11], v[12:13]
	s_nop 0
	v_cvt_pk_bf16_f32 v205, v10, v11
	v_mul_f32_e32 v8, 0xbfb8aa3b, v4
	v_mul_f32_e32 v9, 0xbfb8aa3b, v5
	v_exp_f32_e32 v8, v8
	v_exp_f32_e32 v9, v9
	s_nop 0
	v_pk_add_f32 v[8:9], v[8:9], 1.0 op_sel_hi:[1,0]
	s_nop 0
	v_rcp_f32_e32 v10, v9
	s_nop 0
	v_mul_f32_e32 v5, v5, v10
	v_mul_f32_e32 v11, 0xbfb8aa3b, v7
	v_mul_f32_e32 v10, 0xbfb8aa3b, v6
	v_exp_f32_e32 v10, v10
	v_exp_f32_e32 v11, v11
	v_rcp_f32_e32 v9, v8
	s_nop 0
	v_mul_f32_e32 v4, v4, v9
	v_pk_add_f32 v[10:11], v[10:11], 1.0 op_sel_hi:[1,0]
	v_pk_mul_f32 v[0:1], v[0:1], v[4:5]
	s_nop 0
	v_cvt_pk_bf16_f32 v206, v0, v1
	v_div_scale_f32 v8, s[30:31], v10, v10, v6
	v_rcp_f32_e32 v1, v11
	s_nop 0
	v_mul_f32_e32 v5, v7, v1
	v_rcp_f32_e32 v1, v10
	s_nop 0
	v_mul_f32_e32 v4, v6, v1
	v_pk_mul_f32 v[2:3], v[2:3], v[4:5]
	s_nop 0
	v_cvt_pk_bf16_f32 v207, v2, v3
	s_nop 1
	v_permlane16_swap_b32_e32 v204, v206
	v_permlane16_swap_b32_e32 v205, v207
	global_store_dwordx4 v[40:41], v[204:207], off offset:128
	s_andn2_b64 vcc, exec, s[0:1]
	s_mov_b32 s56, s54
	s_mov_b32 s38, s55
	s_cbranch_vccz .LBB0_695

.LBB0_1800:
	s_or_b64 exec, exec, s[38:39]
	v_bfe_u32 v208, v154, 4, 1
	v_mul_u32_u24_e32 v208, 0x15ff8, v208
	v_mov_b32_e32 v209, 0
	v_mul_f32_e32 v131, 0xbfb8aa3b, v124
	v_exp_f32_e32 v132, v131
	v_mul_f32_e32 v131, 0xbfb8aa3b, v125
	v_exp_f32_e32 v133, v131
	v_or_b32_e32 v130, s30, v152
	s_lshl_b32 s38, s56, 7
	v_lshlrev_b32_e32 v131, 4, v145
	v_pk_add_f32 v[132:133], v[132:133], 1.0 op_sel_hi:[1,0]
	v_lshlrev_b32_e32 v134, 2, v144
	v_or3_b32 v134, v131, s38, v134
	v_add_u32_e32 v130, v130, v153
	v_ashrrev_i32_e32 v135, 31, v134
	v_div_scale_f32 v139, s[30:31], v132, v132, v124
	v_rcp_f32_e32 v140, v139
	v_rcp_f32_e32 v131, v133
	s_nop 0
	v_mul_f32_e32 v125, v125, v131
	v_fma_f32 v131, -v139, v140, 1.0
	v_fmac_f32_e32 v140, v131, v140
	v_mul_f32_e32 v136, 0xbfb8aa3b, v126
	v_mul_f32_e32 v137, 0xbfb8aa3b, v127
	v_exp_f32_e32 v136, v136
	v_exp_f32_e32 v137, v137
	v_rcp_f32_e32 v131, v132
	s_nop 0
	v_mul_f32_e32 v124, v124, v131
	v_pk_add_f32 v[136:137], v[136:137], 1.0 op_sel_hi:[1,0]
	v_pk_mul_f32 v[120:121], v[120:121], v[124:125]
	v_div_scale_f32 v133, s[30:31], v137, v137, v127
	v_rcp_f32_e32 v138, v133
	v_cvt_pk_bf16_f32 v176, v120, v121
	v_fma_f32 v120, -v133, v138, 1.0
	v_fmac_f32_e32 v138, v120, v138
	v_rcp_f32_e32 v120, v137
	s_nop 0
	v_mul_f32_e32 v121, v127, v120
	v_rcp_f32_e32 v120, v136
	s_nop 0
	v_mul_f32_e32 v120, v126, v120
	v_pk_mul_f32 v[120:121], v[122:123], v[120:121]
	v_lshlrev_b64 v[122:123], 1, v[134:135]
	v_cvt_pk_bf16_f32 v177, v120, v121
	v_mov_b64_e32 v[120:121], s[6:7]
	v_mad_i64_i32 v[124:125], s[30:31], v130, s53, v[120:121]
	v_lshl_add_u64 v[124:125], v[124:125], 0, v[122:123]
	v_lshl_add_u64 v[124:125], v[124:125], 0, v[208:209]
	v_mul_f32_e32 v126, 0xbfb8aa3b, v116
	v_mul_f32_e32 v127, 0xbfb8aa3b, v117
	v_exp_f32_e32 v126, v126
	v_exp_f32_e32 v127, v127
	v_or_b32_e32 v134, 16, v130
	v_pk_add_f32 v[126:127], v[126:127], 1.0 op_sel_hi:[1,0]
	s_nop 0
	v_div_scale_f32 v136, s[30:31], v126, v126, v116
	v_rcp_f32_e32 v137, v136
	v_rcp_f32_e32 v131, v127
	s_nop 0
	v_mul_f32_e32 v117, v117, v131
	v_fma_f32 v127, -v136, v137, 1.0
	v_fmac_f32_e32 v137, v127, v137
	v_mul_f32_e32 v132, 0xbfb8aa3b, v118
	v_mul_f32_e32 v133, 0xbfb8aa3b, v119
	v_exp_f32_e32 v132, v132
	v_exp_f32_e32 v133, v133
	v_rcp_f32_e32 v127, v126
	s_nop 0
	v_mul_f32_e32 v116, v116, v127
	v_pk_add_f32 v[132:133], v[132:133], 1.0 op_sel_hi:[1,0]
	v_pk_mul_f32 v[112:113], v[112:113], v[116:117]
	v_div_scale_f32 v131, s[30:31], v133, v133, v119
	v_rcp_f32_e32 v135, v131
	v_cvt_pk_bf16_f32 v178, v112, v113
	v_fma_f32 v112, -v131, v135, 1.0
	v_fmac_f32_e32 v135, v112, v135
	v_rcp_f32_e32 v112, v133
	s_nop 0
	v_mul_f32_e32 v113, v119, v112
	v_rcp_f32_e32 v112, v132
	s_nop 0
	v_mul_f32_e32 v112, v118, v112
	v_pk_mul_f32 v[112:113], v[114:115], v[112:113]
	s_nop 0
	v_cvt_pk_bf16_f32 v179, v112, v113
	s_nop 1
	v_permlane16_swap_b32_e32 v176, v178
	v_permlane16_swap_b32_e32 v177, v179
	global_store_dwordx4 v[124:125], v[176:179], off
	v_mul_f32_e32 v114, 0xbfb8aa3b, v108
	v_mul_f32_e32 v115, 0xbfb8aa3b, v109
	v_exp_f32_e32 v114, v114
	v_exp_f32_e32 v115, v115
	v_or_b32_e32 v118, 32, v130
	v_pk_add_f32 v[114:115], v[114:115], 1.0 op_sel_hi:[1,0]
	s_nop 0
	v_rcp_f32_e32 v116, v115
	s_nop 0
	v_mul_f32_e32 v109, v109, v116
	v_mul_f32_e32 v117, 0xbfb8aa3b, v111
	v_mul_f32_e32 v116, 0xbfb8aa3b, v110
	v_exp_f32_e32 v116, v116
	v_exp_f32_e32 v117, v117
	v_rcp_f32_e32 v115, v114
	s_nop 0
	v_mul_f32_e32 v108, v108, v115
	v_pk_add_f32 v[116:117], v[116:117], 1.0 op_sel_hi:[1,0]
	v_pk_mul_f32 v[104:105], v[104:105], v[108:109]
	s_nop 0
	v_cvt_pk_bf16_f32 v180, v104, v105
	v_rcp_f32_e32 v104, v117
	s_nop 0
	v_mul_f32_e32 v105, v111, v104
	v_rcp_f32_e32 v104, v116
	s_nop 0
	v_mul_f32_e32 v104, v110, v104
	v_pk_mul_f32 v[104:105], v[106:107], v[104:105]
	s_nop 0
	v_cvt_pk_bf16_f32 v181, v104, v105
	v_mad_i64_i32 v[104:105], s[30:31], v118, s53, v[120:121]
	v_lshl_add_u64 v[104:105], v[104:105], 0, v[122:123]
	v_lshl_add_u64 v[104:105], v[104:105], 0, v[208:209]
	v_mul_f32_e32 v106, 0xbfb8aa3b, v100
	v_mul_f32_e32 v107, 0xbfb8aa3b, v101
	v_exp_f32_e32 v106, v106
	v_exp_f32_e32 v107, v107
	v_or_b32_e32 v110, 48, v130
	v_pk_add_f32 v[106:107], v[106:107], 1.0 op_sel_hi:[1,0]
	s_nop 0
	v_rcp_f32_e32 v108, v107
	s_nop 0
	v_mul_f32_e32 v101, v101, v108
	v_mul_f32_e32 v109, 0xbfb8aa3b, v103
	v_mul_f32_e32 v108, 0xbfb8aa3b, v102
	v_exp_f32_e32 v108, v108
	v_exp_f32_e32 v109, v109
	v_rcp_f32_e32 v107, v106
	s_nop 0
	v_mul_f32_e32 v100, v100, v107
	v_pk_add_f32 v[108:109], v[108:109], 1.0 op_sel_hi:[1,0]
	v_pk_mul_f32 v[96:97], v[96:97], v[100:101]
	s_nop 0
	v_cvt_pk_bf16_f32 v182, v96, v97
	v_rcp_f32_e32 v96, v109
	s_nop 0
	v_mul_f32_e32 v97, v103, v96
	v_rcp_f32_e32 v96, v108
	s_nop 0
	v_mul_f32_e32 v96, v102, v96
	v_pk_mul_f32 v[96:97], v[98:99], v[96:97]
	s_nop 0
	v_cvt_pk_bf16_f32 v183, v96, v97
	s_nop 1
	v_permlane16_swap_b32_e32 v180, v182
	v_permlane16_swap_b32_e32 v181, v183
	global_store_dwordx4 v[104:105], v[180:183], off
	v_mul_f32_e32 v98, 0xbfb8aa3b, v92
	v_mul_f32_e32 v99, 0xbfb8aa3b, v93
	v_exp_f32_e32 v98, v98
	v_exp_f32_e32 v99, v99
	s_nop 0
	v_pk_add_f32 v[98:99], v[98:99], 1.0 op_sel_hi:[1,0]
	s_nop 0
	v_rcp_f32_e32 v100, v99
	s_nop 0
	v_mul_f32_e32 v93, v93, v100
	v_mul_f32_e32 v101, 0xbfb8aa3b, v95
	v_mul_f32_e32 v100, 0xbfb8aa3b, v94
	v_exp_f32_e32 v100, v100
	v_exp_f32_e32 v101, v101
	v_rcp_f32_e32 v99, v98
	s_nop 0
	v_mul_f32_e32 v92, v92, v99
	v_pk_add_f32 v[100:101], v[100:101], 1.0 op_sel_hi:[1,0]
	v_pk_mul_f32 v[88:89], v[88:89], v[92:93]
	s_nop 0
	v_cvt_pk_bf16_f32 v184, v88, v89
	v_rcp_f32_e32 v89, v101
	s_nop 0
	v_mul_f32_e32 v93, v95, v89
	v_rcp_f32_e32 v89, v100
	s_nop 0
	v_mul_f32_e32 v92, v94, v89
	v_pk_mul_f32 v[90:91], v[90:91], v[92:93]
	s_nop 0
	v_cvt_pk_bf16_f32 v185, v90, v91
	v_mul_f32_e32 v88, 0xbfb8aa3b, v84
	v_mul_f32_e32 v89, 0xbfb8aa3b, v85
	v_exp_f32_e32 v88, v88
	v_exp_f32_e32 v89, v89
	s_nop 0
	v_pk_add_f32 v[88:89], v[88:89], 1.0 op_sel_hi:[1,0]
	s_nop 0
	v_rcp_f32_e32 v90, v89
	s_nop 0
	v_mul_f32_e32 v85, v85, v90
	v_mul_f32_e32 v91, 0xbfb8aa3b, v87
	v_mul_f32_e32 v90, 0xbfb8aa3b, v86
	v_exp_f32_e32 v90, v90
	v_exp_f32_e32 v91, v91
	v_rcp_f32_e32 v89, v88
	s_nop 0
	v_mul_f32_e32 v84, v84, v89
	v_pk_add_f32 v[90:91], v[90:91], 1.0 op_sel_hi:[1,0]
	v_pk_mul_f32 v[80:81], v[80:81], v[84:85]
	s_nop 0
	v_cvt_pk_bf16_f32 v186, v80, v81
	v_rcp_f32_e32 v81, v91
	s_nop 0
	v_mul_f32_e32 v85, v87, v81
	v_rcp_f32_e32 v81, v90
	s_nop 0
	v_mul_f32_e32 v84, v86, v81
	v_pk_mul_f32 v[82:83], v[82:83], v[84:85]
	s_nop 0
	v_cvt_pk_bf16_f32 v187, v82, v83
	s_nop 1
	v_permlane16_swap_b32_e32 v184, v186
	v_permlane16_swap_b32_e32 v185, v187
	global_store_dwordx4 v[124:125], v[184:187], off offset:128
	v_mul_f32_e32 v80, 0xbfb8aa3b, v76
	v_mul_f32_e32 v81, 0xbfb8aa3b, v77
	v_exp_f32_e32 v80, v80
	v_exp_f32_e32 v81, v81
	s_nop 0
	v_pk_add_f32 v[80:81], v[80:81], 1.0 op_sel_hi:[1,0]
	s_nop 0
	v_rcp_f32_e32 v82, v81
	s_nop 0
	v_mul_f32_e32 v77, v77, v82
	v_mul_f32_e32 v83, 0xbfb8aa3b, v79
	v_mul_f32_e32 v82, 0xbfb8aa3b, v78
	v_exp_f32_e32 v82, v82
	v_exp_f32_e32 v83, v83
	v_rcp_f32_e32 v81, v80
	s_nop 0
	v_mul_f32_e32 v76, v76, v81
	v_pk_add_f32 v[82:83], v[82:83], 1.0 op_sel_hi:[1,0]
	v_pk_mul_f32 v[72:73], v[72:73], v[76:77]
	s_nop 0
	v_cvt_pk_bf16_f32 v188, v72, v73
	v_rcp_f32_e32 v73, v83
	s_nop 0
	v_mul_f32_e32 v77, v79, v73
	v_rcp_f32_e32 v73, v82
	s_nop 0
	v_mul_f32_e32 v76, v78, v73
	v_pk_mul_f32 v[74:75], v[74:75], v[76:77]
	s_nop 0
	v_cvt_pk_bf16_f32 v189, v74, v75
	v_mul_f32_e32 v72, 0xbfb8aa3b, v68
	v_mul_f32_e32 v73, 0xbfb8aa3b, v69
	v_exp_f32_e32 v72, v72
	v_exp_f32_e32 v73, v73
	s_nop 0
	v_pk_add_f32 v[72:73], v[72:73], 1.0 op_sel_hi:[1,0]
	s_nop 0
	v_rcp_f32_e32 v74, v73
	s_nop 0
	v_mul_f32_e32 v69, v69, v74
	v_mul_f32_e32 v75, 0xbfb8aa3b, v71
	v_mul_f32_e32 v74, 0xbfb8aa3b, v70
	v_exp_f32_e32 v74, v74
	v_exp_f32_e32 v75, v75
	v_rcp_f32_e32 v73, v72
	s_nop 0
	v_mul_f32_e32 v68, v68, v73
	v_pk_add_f32 v[74:75], v[74:75], 1.0 op_sel_hi:[1,0]
	v_pk_mul_f32 v[64:65], v[64:65], v[68:69]
	s_nop 0
	v_cvt_pk_bf16_f32 v190, v64, v65
	v_rcp_f32_e32 v65, v75
	s_nop 0
	v_mul_f32_e32 v69, v71, v65
	v_rcp_f32_e32 v65, v74
	s_nop 0
	v_mul_f32_e32 v68, v70, v65
	v_pk_mul_f32 v[66:67], v[66:67], v[68:69]
	s_nop 0
	v_cvt_pk_bf16_f32 v191, v66, v67
	s_nop 1
	v_permlane16_swap_b32_e32 v188, v190
	v_permlane16_swap_b32_e32 v189, v191
	global_store_dwordx4 v[104:105], v[188:191], off offset:128
	v_mul_f32_e32 v64, 0xbfb8aa3b, v60
	v_mul_f32_e32 v65, 0xbfb8aa3b, v61
	v_exp_f32_e32 v64, v64
	v_exp_f32_e32 v65, v65
	v_add_u32_e32 v68, 0x80, v130
	v_pk_add_f32 v[64:65], v[64:65], 1.0 op_sel_hi:[1,0]
	s_nop 0
	v_rcp_f32_e32 v66, v65
	s_nop 0
	v_mul_f32_e32 v61, v61, v66
	v_mul_f32_e32 v67, 0xbfb8aa3b, v63
	v_mul_f32_e32 v66, 0xbfb8aa3b, v62
	v_exp_f32_e32 v66, v66
	v_exp_f32_e32 v67, v67
	v_rcp_f32_e32 v65, v64
	s_nop 0
	v_mul_f32_e32 v60, v60, v65
	v_pk_add_f32 v[66:67], v[66:67], 1.0 op_sel_hi:[1,0]
	v_pk_mul_f32 v[56:57], v[56:57], v[60:61]
	s_nop 0
	v_cvt_pk_bf16_f32 v192, v56, v57
	v_rcp_f32_e32 v56, v67
	s_nop 0
	v_mul_f32_e32 v57, v63, v56
	v_rcp_f32_e32 v56, v66
	s_nop 0
	v_mul_f32_e32 v56, v62, v56
	v_pk_mul_f32 v[56:57], v[58:59], v[56:57]
	s_nop 0
	v_cvt_pk_bf16_f32 v193, v56, v57
	v_mad_i64_i32 v[56:57], s[30:31], v68, s53, v[120:121]
	v_lshl_add_u64 v[56:57], v[56:57], 0, v[122:123]
	v_lshl_add_u64 v[56:57], v[56:57], 0, v[208:209]
	v_mul_f32_e32 v58, 0xbfb8aa3b, v52
	v_mul_f32_e32 v59, 0xbfb8aa3b, v53
	v_exp_f32_e32 v58, v58
	v_exp_f32_e32 v59, v59
	v_add_u32_e32 v62, 0x90, v130
	v_pk_add_f32 v[58:59], v[58:59], 1.0 op_sel_hi:[1,0]
	s_nop 0
	v_rcp_f32_e32 v60, v59
	s_nop 0
	v_mul_f32_e32 v53, v53, v60
	v_mul_f32_e32 v61, 0xbfb8aa3b, v55
	v_mul_f32_e32 v60, 0xbfb8aa3b, v54
	v_exp_f32_e32 v60, v60
	v_exp_f32_e32 v61, v61
	v_rcp_f32_e32 v59, v58
	s_nop 0
	v_mul_f32_e32 v52, v52, v59
	v_pk_add_f32 v[60:61], v[60:61], 1.0 op_sel_hi:[1,0]
	v_pk_mul_f32 v[48:49], v[48:49], v[52:53]
	s_nop 0
	v_cvt_pk_bf16_f32 v194, v48, v49
	v_rcp_f32_e32 v48, v61
	s_nop 0
	v_mul_f32_e32 v49, v55, v48
	v_rcp_f32_e32 v48, v60
	s_nop 0
	v_mul_f32_e32 v48, v54, v48
	v_pk_mul_f32 v[48:49], v[50:51], v[48:49]
	s_nop 0
	v_cvt_pk_bf16_f32 v195, v48, v49
	s_nop 1
	v_permlane16_swap_b32_e32 v192, v194
	v_permlane16_swap_b32_e32 v193, v195
	global_store_dwordx4 v[56:57], v[192:195], off
	v_mul_f32_e32 v50, 0xbfb8aa3b, v44
	v_mul_f32_e32 v51, 0xbfb8aa3b, v45
	v_exp_f32_e32 v50, v50
	v_exp_f32_e32 v51, v51
	v_add_u32_e32 v54, 0xa0, v130
	v_pk_add_f32 v[50:51], v[50:51], 1.0 op_sel_hi:[1,0]
	s_nop 0
	v_rcp_f32_e32 v52, v51
	s_nop 0
	v_mul_f32_e32 v45, v45, v52
	v_mul_f32_e32 v53, 0xbfb8aa3b, v47
	v_mul_f32_e32 v52, 0xbfb8aa3b, v46
	v_exp_f32_e32 v52, v52
	v_exp_f32_e32 v53, v53
	v_rcp_f32_e32 v51, v50
	s_nop 0
	v_mul_f32_e32 v44, v44, v51
	v_pk_add_f32 v[52:53], v[52:53], 1.0 op_sel_hi:[1,0]
	v_pk_mul_f32 v[40:41], v[40:41], v[44:45]
	s_nop 0
	v_cvt_pk_bf16_f32 v196, v40, v41
	v_rcp_f32_e32 v40, v53
	s_nop 0
	v_mul_f32_e32 v41, v47, v40
	v_rcp_f32_e32 v40, v52
	s_nop 0
	v_mul_f32_e32 v40, v46, v40
	v_pk_mul_f32 v[40:41], v[42:43], v[40:41]
	s_nop 0
	v_cvt_pk_bf16_f32 v197, v40, v41
	v_mad_i64_i32 v[40:41], s[30:31], v54, s53, v[120:121]
	v_lshl_add_u64 v[40:41], v[40:41], 0, v[122:123]
	v_lshl_add_u64 v[40:41], v[40:41], 0, v[208:209]
	v_mul_f32_e32 v42, 0xbfb8aa3b, v36
	v_mul_f32_e32 v43, 0xbfb8aa3b, v37
	v_exp_f32_e32 v42, v42
	v_exp_f32_e32 v43, v43
	v_add_u32_e32 v46, 0xb0, v130
	v_pk_add_f32 v[42:43], v[42:43], 1.0 op_sel_hi:[1,0]
	s_nop 0
	v_rcp_f32_e32 v44, v43
	s_nop 0
	v_mul_f32_e32 v37, v37, v44
	v_mul_f32_e32 v45, 0xbfb8aa3b, v39
	v_mul_f32_e32 v44, 0xbfb8aa3b, v38
	v_exp_f32_e32 v44, v44
	v_exp_f32_e32 v45, v45
	v_rcp_f32_e32 v43, v42
	s_nop 0
	v_mul_f32_e32 v36, v36, v43
	v_pk_add_f32 v[44:45], v[44:45], 1.0 op_sel_hi:[1,0]
	v_pk_mul_f32 v[32:33], v[32:33], v[36:37]
	s_nop 0
	v_cvt_pk_bf16_f32 v198, v32, v33
	v_rcp_f32_e32 v32, v45
	s_nop 0
	v_mul_f32_e32 v33, v39, v32
	v_rcp_f32_e32 v32, v44
	s_nop 0
	v_mul_f32_e32 v32, v38, v32
	v_pk_mul_f32 v[32:33], v[34:35], v[32:33]
	s_nop 0
	v_cvt_pk_bf16_f32 v199, v32, v33
	s_nop 1
	v_permlane16_swap_b32_e32 v196, v198
	v_permlane16_swap_b32_e32 v197, v199
	global_store_dwordx4 v[40:41], v[196:199], off
	v_mul_f32_e32 v34, 0xbfb8aa3b, v28
	v_mul_f32_e32 v35, 0xbfb8aa3b, v29
	v_exp_f32_e32 v34, v34
	v_exp_f32_e32 v35, v35
	s_nop 0
	v_pk_add_f32 v[34:35], v[34:35], 1.0 op_sel_hi:[1,0]
	s_nop 0
	v_rcp_f32_e32 v36, v35
	s_nop 0
	v_mul_f32_e32 v29, v29, v36
	v_mul_f32_e32 v37, 0xbfb8aa3b, v31
	v_mul_f32_e32 v36, 0xbfb8aa3b, v30
	v_exp_f32_e32 v36, v36
	v_exp_f32_e32 v37, v37
	v_rcp_f32_e32 v35, v34
	s_nop 0
	v_mul_f32_e32 v28, v28, v35
	v_pk_add_f32 v[36:37], v[36:37], 1.0 op_sel_hi:[1,0]
	v_pk_mul_f32 v[24:25], v[24:25], v[28:29]
	s_nop 0
	v_cvt_pk_bf16_f32 v200, v24, v25
	v_rcp_f32_e32 v25, v37
	s_nop 0
	v_mul_f32_e32 v29, v31, v25
	v_rcp_f32_e32 v25, v36
	s_nop 0
	v_mul_f32_e32 v28, v30, v25
	v_pk_mul_f32 v[26:27], v[26:27], v[28:29]
	s_nop 0
	v_cvt_pk_bf16_f32 v201, v26, v27
	v_mul_f32_e32 v24, 0xbfb8aa3b, v20
	v_mul_f32_e32 v25, 0xbfb8aa3b, v21
	v_exp_f32_e32 v24, v24
	v_exp_f32_e32 v25, v25
	s_nop 0
	v_pk_add_f32 v[24:25], v[24:25], 1.0 op_sel_hi:[1,0]
	s_nop 0
	v_rcp_f32_e32 v26, v25
	s_nop 0
	v_mul_f32_e32 v21, v21, v26
	v_mul_f32_e32 v27, 0xbfb8aa3b, v23
	v_mul_f32_e32 v26, 0xbfb8aa3b, v22
	v_exp_f32_e32 v26, v26
	v_exp_f32_e32 v27, v27
	v_rcp_f32_e32 v25, v24
	s_nop 0
	v_mul_f32_e32 v20, v20, v25
	v_pk_add_f32 v[26:27], v[26:27], 1.0 op_sel_hi:[1,0]
	v_pk_mul_f32 v[16:17], v[16:17], v[20:21]
	s_nop 0
	v_cvt_pk_bf16_f32 v202, v16, v17
	v_rcp_f32_e32 v17, v27
	s_nop 0
	v_mul_f32_e32 v21, v23, v17
	v_rcp_f32_e32 v17, v26
	s_nop 0
	v_mul_f32_e32 v20, v22, v17
	v_pk_mul_f32 v[18:19], v[18:19], v[20:21]
	s_nop 0
	v_cvt_pk_bf16_f32 v203, v18, v19
	s_nop 1
	v_permlane16_swap_b32_e32 v200, v202
	v_permlane16_swap_b32_e32 v201, v203
	global_store_dwordx4 v[56:57], v[200:203], off offset:128
	v_mul_f32_e32 v16, 0xbfb8aa3b, v12
	v_mul_f32_e32 v17, 0xbfb8aa3b, v13
	v_exp_f32_e32 v16, v16
	v_exp_f32_e32 v17, v17
	s_nop 0
	v_pk_add_f32 v[16:17], v[16:17], 1.0 op_sel_hi:[1,0]
	s_nop 0
	v_rcp_f32_e32 v18, v17
	s_nop 0
	v_mul_f32_e32 v13, v13, v18
	v_mul_f32_e32 v19, 0xbfb8aa3b, v15
	v_mul_f32_e32 v18, 0xbfb8aa3b, v14
	v_exp_f32_e32 v18, v18
	v_exp_f32_e32 v19, v19
	v_rcp_f32_e32 v17, v16
	s_nop 0
	v_mul_f32_e32 v12, v12, v17
	v_pk_add_f32 v[18:19], v[18:19], 1.0 op_sel_hi:[1,0]
	v_pk_mul_f32 v[8:9], v[8:9], v[12:13]
	s_nop 0
	v_cvt_pk_bf16_f32 v204, v8, v9
	v_rcp_f32_e32 v9, v19
	s_nop 0
	v_mul_f32_e32 v13, v15, v9
	v_rcp_f32_e32 v9, v18
	s_nop 0
	v_mul_f32_e32 v12, v14, v9
	v_pk_mul_f32 v[10:11], v[10:11], v[12:13]
	s_nop 0
	v_cvt_pk_bf16_f32 v205, v10, v11
	v_mul_f32_e32 v8, 0xbfb8aa3b, v4
	v_mul_f32_e32 v9, 0xbfb8aa3b, v5
	v_exp_f32_e32 v8, v8
	v_exp_f32_e32 v9, v9
	s_nop 0
	v_pk_add_f32 v[8:9], v[8:9], 1.0 op_sel_hi:[1,0]
	s_nop 0
	v_rcp_f32_e32 v10, v9
	s_nop 0
	v_mul_f32_e32 v5, v5, v10
	v_mul_f32_e32 v11, 0xbfb8aa3b, v7
	v_mul_f32_e32 v10, 0xbfb8aa3b, v6
	v_exp_f32_e32 v10, v10
	v_exp_f32_e32 v11, v11
	v_rcp_f32_e32 v9, v8
	s_nop 0
	v_mul_f32_e32 v4, v4, v9
	v_pk_add_f32 v[10:11], v[10:11], 1.0 op_sel_hi:[1,0]
	v_pk_mul_f32 v[0:1], v[0:1], v[4:5]
	s_nop 0
	v_cvt_pk_bf16_f32 v206, v0, v1
	v_div_scale_f32 v8, s[30:31], v10, v10, v6
	v_rcp_f32_e32 v1, v11
	s_nop 0
	v_mul_f32_e32 v5, v7, v1
	v_rcp_f32_e32 v1, v10
	s_nop 0
	v_mul_f32_e32 v4, v6, v1
	v_pk_mul_f32 v[2:3], v[2:3], v[4:5]
	s_nop 0
	v_cvt_pk_bf16_f32 v207, v2, v3
	s_nop 1
	v_permlane16_swap_b32_e32 v204, v206
	v_permlane16_swap_b32_e32 v205, v207
	global_store_dwordx4 v[40:41], v[204:207], off offset:128
	s_andn2_b64 vcc, exec, s[0:1]
	s_mov_b32 s56, s54
	s_mov_b32 s38, s55
	s_cbranch_vccz .LBB0_1809
